# w_out/down GEMM: run-time CU map, the two workgroups resident on one CU take tiles with the same 128 A rows and adjacent column tiles (L1 reuse)
# speedup vs baseline: 1.0435x; 1.0022x over previous
.LBB0_2:
	s_or_b64 exec, exec, s[6:7]
	s_waitcnt lgkmcnt(0)
	s_barrier
	s_add_u32 s4, s62, 0x15e01000
	s_getreg_b32 s3, hwreg(HW_REG_XCC_ID, 0, 4)
	s_addc_u32 s5, s63, 0
	s_and_b32 s8, s3, 15
	s_mov_b64 s[12:13], exec
	v_readlane_b32 s6, v252, 0
	v_readlane_b32 s7, v252, 1
	s_and_b64 s[6:7], s[12:13], s[6:7]
	s_mov_b64 exec, s[6:7]
	s_cbranch_execz .LBB0_5
	s_mov_b64 s[6:7], exec
	v_mbcnt_lo_u32_b32 v1, s6, 0
	v_mbcnt_hi_u32_b32 v1, s7, v1
	v_cmp_eq_u32_e32 vcc, 0, v1
	s_and_b64 s[10:11], exec, vcc
	s_mov_b64 exec, s[10:11]
	s_cbranch_execz .LBB0_5
	s_lshl_b32 s9, s8, 8
	s_bcnt1_i32_b64 s6, s[6:7]
	v_mov_b32_e32 v1, s9
	v_mov_b32_e32 v2, s6
	global_atomic_add v1, v2, s[4:5] offset:1024
	s_and_b32 s9, s2, 7
	s_lshl_b32 s9, s9, 2
	s_addk_i32 s9, 0x3600
	s_lshl_b32 s6, 1, s8
	v_mov_b32_e32 v1, s9
	v_mov_b32_e32 v2, s6
	global_atomic_or v1, v2, s[4:5]
	s_getreg_b32 s6, hwreg(HW_REG_HW_ID, 8, 8)
	s_and_b32 s9, s8, 7
	s_lshl_b32 s9, s9, 8
	s_or_b32 s9, s9, s6
	s_and_b32 s7, s9, 3
	s_lshl_b32 s7, s7, 3
	s_and_b32 s9, s9, 0x7fc
	s_addk_i32 s9, 0x3700
	s_lshl_b32 s6, 1, s7
	v_mov_b32_e32 v1, s9
	v_mov_b32_e32 v2, s6
	global_atomic_add v1, v1, v2, s[4:5] sc0
	s_waitcnt vmcnt(0)
	v_readfirstlane_b32 s6, v1
	s_lshr_b32 s6, s6, s7
	s_and_b32 s6, s6, 0xff
	v_mov_b32_e32 v1, 0x12ff8
	v_mov_b32_e32 v2, s6
	ds_write_b32 v1, v2
	s_waitcnt lgkmcnt(0)
.LBB0_5:
	s_or_b64 exec, exec, s[12:13]
	s_load_dwordx2 s[6:7], s[0:1], 0xd0
	s_waitcnt lgkmcnt(0)
	s_cmp_ge_i32 s6, s7
	s_cbranch_scc1 .LBB0_549
	s_add_u32 s10, s0, 0xd8
	s_addc_u32 s11, s1, 0
	v_writelane_b32 v252, s10, 2
	s_load_dwordx16 s[36:51], s[0:1], 0x0
	v_mbcnt_lo_u32_b32 v2, -1, 0
	v_writelane_b32 v252, s11, 3
	s_add_u32 s10, s62, 0x15e01200
	s_addc_u32 s11, s63, 0
	v_writelane_b32 v252, s10, 4
	s_mov_b32 s17, s6
	v_mov_b32_e32 v131, 0
	v_writelane_b32 v252, s11, 5
	s_add_u32 s10, s62, 0x15e01400
	s_addc_u32 s11, s63, 0
	v_writelane_b32 v252, s10, 6
	v_mov_b32_e32 v1, 1
	v_mov_b32_e32 v197, 0x358637bd
	v_writelane_b32 v252, s11, 7
	s_add_u32 s10, s62, 0x15e01500
	s_addc_u32 s11, s63, 0
	v_writelane_b32 v252, s10, 8
	v_mbcnt_hi_u32_b32 v198, -1, v2
	v_mov_b32_e32 v199, 0x3ff
	v_writelane_b32 v252, s11, 9
	s_add_u32 s10, s62, 0x15e01600
	s_addc_u32 s11, s63, 0
	v_writelane_b32 v252, s10, 10
	v_mov_b32_e32 v200, 0xc000
	v_mov_b32_e32 v203, 0x41b17218
	v_writelane_b32 v252, s11, 11
	s_add_u32 s10, s62, 0x15e01700
	s_addc_u32 s11, s63, 0
	v_writelane_b32 v252, s10, 12
	v_mov_b32_e32 v204, 0x6000
	s_movk_i32 s33, 0x1000
	v_writelane_b32 v252, s11, 13
	s_add_u32 s10, s62, 0x15e01800
	s_addc_u32 s11, s63, 0
	v_writelane_b32 v252, s10, 14
	s_movk_i32 s26, 0x7fff
	s_movk_i32 s85, 0x104
	v_writelane_b32 v252, s11, 15
	s_add_u32 s10, s62, 0x15e01900
	s_addc_u32 s11, s63, 0
	v_writelane_b32 v252, s10, 16
	s_movk_i32 s12, 0xc00
	s_movk_i32 s15, 0x28c0
	v_writelane_b32 v252, s11, 17
	s_add_u32 s10, s62, 0x15e01a00
	s_addc_u32 s11, s63, 0
	v_writelane_b32 v252, s10, 18
	s_mov_b32 s14, 0x800000
	s_mov_b32 s18, 0x3e38aa3b
	v_writelane_b32 v252, s11, 19
	s_add_u32 s10, s62, 0x15e01b00
	s_addc_u32 s11, s63, 0
	v_writelane_b32 v252, s10, 20
	s_mov_b32 s19, 0xffff0000
	s_movk_i32 s23, 0x110
	v_writelane_b32 v252, s11, 21
	s_add_u32 s10, s62, 0x15e01c00
	s_addc_u32 s11, s63, 0
	v_writelane_b32 v252, s10, 22
	s_mov_b32 s93, 0
	s_mov_b64 s[98:99], 0x80
	v_writelane_b32 v252, s11, 23
	s_add_u32 s10, s62, 0x15e01d00
	s_addc_u32 s11, s63, 0
	v_writelane_b32 v252, s10, 24
	s_mov_b64 s[70:71], 0x100
	s_mov_b64 s[72:73], 0x180
	v_writelane_b32 v252, s11, 25
	s_add_u32 s10, s62, 0x15e01e00
	s_addc_u32 s11, s63, 0
	v_writelane_b32 v252, s10, 26
	s_mov_b64 s[74:75], 0x200
	s_mov_b64 s[76:77], 0x280
	v_writelane_b32 v252, s11, 27
	s_add_u32 s10, s62, 0x15e01f00
	s_addc_u32 s11, s63, 0
	v_writelane_b32 v252, s10, 28
	s_mov_b64 s[78:79], 0x300
	s_mov_b64 s[80:81], 0x380
	v_writelane_b32 v252, s11, 29
	s_add_u32 s10, s62, 0x15e02000
	s_addc_u32 s11, s63, 0
	v_writelane_b32 v252, s10, 30
	s_mov_b64 s[90:91], 0x400
	s_mov_b64 s[82:83], 0x780
	v_writelane_b32 v252, s11, 31
	s_add_u32 s10, s62, 0x15e02100
	s_addc_u32 s11, s63, 0
	v_writelane_b32 v252, s10, 32
	s_nop 1
	v_writelane_b32 v252, s11, 33
	s_add_u32 s10, s62, 0x15e02200
	s_addc_u32 s11, s63, 0
	v_writelane_b32 v252, s10, 34
	s_nop 1
	v_writelane_b32 v252, s11, 35
	s_add_u32 s10, s62, 0x15e02300
	s_addc_u32 s11, s63, 0
	v_writelane_b32 v252, s10, 36
	s_cmp_eq_u32 s8, 15
	s_nop 0
	v_writelane_b32 v252, s11, 37
	s_cselect_b64 s[10:11], -1, 0
	v_writelane_b32 v252, s10, 38
	s_cmp_eq_u32 s8, 14
	s_nop 0
	v_writelane_b32 v252, s11, 39
	s_cselect_b64 s[10:11], -1, 0
	v_writelane_b32 v252, s10, 40
	s_cmp_eq_u32 s8, 13
	s_nop 0
	v_writelane_b32 v252, s11, 41
	s_cselect_b64 s[10:11], -1, 0
	v_writelane_b32 v252, s10, 42
	s_cmp_eq_u32 s8, 12
	s_nop 0
	v_writelane_b32 v252, s11, 43
	s_cselect_b64 s[10:11], -1, 0
	v_writelane_b32 v252, s10, 44
	s_cmp_eq_u32 s8, 11
	s_nop 0
	v_writelane_b32 v252, s11, 45
	s_cselect_b64 s[10:11], -1, 0
	v_writelane_b32 v252, s10, 46
	s_cmp_eq_u32 s8, 10
	s_nop 0
	v_writelane_b32 v252, s11, 47
	s_cselect_b64 s[10:11], -1, 0
	v_writelane_b32 v252, s10, 48
	s_cmp_eq_u32 s8, 9
	s_nop 0
	v_writelane_b32 v252, s11, 49
	s_cselect_b64 s[10:11], -1, 0
	v_writelane_b32 v252, s10, 50
	s_cmp_eq_u32 s8, 8
	s_nop 0
	v_writelane_b32 v252, s11, 51
	s_cselect_b64 s[10:11], -1, 0
	v_writelane_b32 v252, s10, 52
	s_cmp_eq_u32 s8, 7
	s_nop 0
	v_writelane_b32 v252, s11, 53
	s_cselect_b64 s[10:11], -1, 0
	v_writelane_b32 v252, s10, 54
	s_cmp_eq_u32 s8, 6
	s_nop 0
	v_writelane_b32 v252, s11, 55
	s_cselect_b64 s[10:11], -1, 0
	v_writelane_b32 v252, s10, 56
	s_cmp_eq_u32 s8, 5
	s_nop 0
	v_writelane_b32 v252, s11, 57
	s_cselect_b64 s[10:11], -1, 0
	v_writelane_b32 v252, s10, 58
	s_cmp_eq_u32 s8, 4
	s_nop 0
	v_writelane_b32 v252, s11, 59
	s_cselect_b64 s[10:11], -1, 0
	v_writelane_b32 v252, s10, 60
	s_cmp_eq_u32 s8, 3
	s_nop 0
	v_writelane_b32 v252, s11, 61
	s_cselect_b64 s[10:11], -1, 0
	v_writelane_b32 v252, s10, 62
	s_cmp_eq_u32 s8, 2
	s_nop 0
	v_writelane_b32 v252, s11, 63
	s_cselect_b64 s[10:11], -1, 0
	v_writelane_b32 v253, s10, 0
	s_cmp_eq_u32 s8, 1
	s_nop 0
	v_writelane_b32 v253, s11, 1
	s_cselect_b64 s[10:11], -1, 0
	v_writelane_b32 v253, s10, 2
	s_cmp_eq_u32 s8, 0
	s_nop 0
	v_writelane_b32 v253, s11, 3
	s_cselect_b64 s[10:11], -1, 0
	s_lshl_b32 s3, s8, 8
	s_add_u32 s4, s4, s3
	s_addc_u32 s3, s5, 0
	v_writelane_b32 v253, s10, 4
	s_add_u32 s8, s4, 0x1400
	s_addc_u32 s9, s3, 0
	v_writelane_b32 v253, s11, 5
	v_writelane_b32 v253, s8, 6
	s_add_u32 s4, s4, 0x2400
	s_addc_u32 s5, s3, 0
	v_writelane_b32 v253, s9, 7
	v_writelane_b32 v253, s4, 8
	s_nop 1
	v_writelane_b32 v253, s5, 9
	s_add_u32 s4, s62, 0x15e04400
	s_addc_u32 s5, s63, 0
	v_writelane_b32 v253, s4, 10
	s_nop 1
	v_writelane_b32 v253, s5, 11
	s_add_u32 s4, s62, 0x15e04500
	s_addc_u32 s5, s63, 0
	v_writelane_b32 v253, s4, 12
	s_nop 1
	v_writelane_b32 v253, s5, 13
	s_add_u32 s4, s62, 0x80000
	s_addc_u32 s5, s63, 0
	v_writelane_b32 v253, s4, 14
	s_nop 1
	v_writelane_b32 v253, s5, 15
	s_add_u32 s4, s62, 0xf680000
	s_addc_u32 s5, s63, 0
	v_writelane_b32 v253, s4, 16
	s_nop 1
	v_writelane_b32 v253, s5, 17
	s_add_u32 s4, s62, 0xe680000
	s_addc_u32 s5, s63, 0
	s_add_u32 s8, s62, 0x2080000
	v_writelane_b32 v253, s4, 18
	s_addc_u32 s9, s63, 0
	s_nop 0
	v_writelane_b32 v253, s5, 19
	s_add_u32 s4, s62, 0x7e00000
	s_addc_u32 s5, s63, 0
	v_writelane_b32 v253, s4, 20
	s_nop 1
	v_writelane_b32 v253, s5, 21
	s_add_u32 s4, s62, 0x9e40000
	s_addc_u32 s5, s63, 0
	v_writelane_b32 v253, s4, 22
	s_nop 1
	v_writelane_b32 v253, s5, 23
	s_add_u32 s4, s62, 0xce80000
	s_addc_u32 s5, s63, 0
	v_writelane_b32 v253, s4, 24
	s_nop 1
	v_writelane_b32 v253, s5, 25
	s_add_u32 s4, s62, 0x1080000
	s_addc_u32 s5, s63, 0
	v_writelane_b32 v253, s4, 26
	s_nop 1
	v_writelane_b32 v253, s5, 27
	s_add_u32 s4, s62, 0xde80000
	s_addc_u32 s5, s63, 0
	s_add_u32 s68, s62, 0x9e80000
	v_writelane_b32 v253, s4, 28
	s_addc_u32 s69, s63, 0
	s_nop 0
	v_writelane_b32 v253, s5, 29
	s_add_u32 s4, s62, 0x9600000
	s_addc_u32 s5, s63, 0
	v_writelane_b32 v253, s4, 30
	s_nop 1
	v_writelane_b32 v253, s5, 31
	s_add_u32 s4, s62, 0x7200000
	s_addc_u32 s5, s63, 0
	v_writelane_b32 v253, s4, 32
	s_nop 1
	v_writelane_b32 v253, s5, 33
	s_add_u32 s4, s62, 0x7c00000
	s_addc_u32 s5, s63, 0
	v_writelane_b32 v253, s4, 34
	s_nop 1
	v_writelane_b32 v253, s5, 35
	s_add_u32 s4, s62, 0x15d81000
	s_addc_u32 s5, s63, 0
	v_writelane_b32 v253, s4, 36
	s_nop 1
	v_writelane_b32 v253, s5, 37
	s_add_u32 s4, s62, 0x15d01000
	s_addc_u32 s5, s63, 0
	v_writelane_b32 v253, s4, 38
	s_nop 1
	v_writelane_b32 v253, s5, 39
	s_add_u32 s4, s62, 0x7a00000
	s_addc_u32 s5, s63, 0
	v_writelane_b32 v253, s4, 40
	s_nop 1
	v_writelane_b32 v253, s5, 41
	s_add_u32 s4, s62, 0x154e0000
	s_addc_u32 s5, s63, 0
	v_writelane_b32 v253, s4, 42
	s_nop 1
	v_writelane_b32 v253, s5, 43
	s_add_u32 s4, s62, 0x15ce0000
	s_addc_u32 s5, s63, 0
	v_writelane_b32 v253, s4, 44
	s_add_u32 s3, s60, 0x3000000
	s_nop 0
	v_writelane_b32 v253, s5, 45
	v_writelane_b32 v253, s3, 46
	s_addc_u32 s3, s61, 0
	s_add_u32 s86, s62, 0x15d00000
	s_addc_u32 s87, s63, 0
	v_writelane_b32 v253, s3, 47
	s_add_u32 s3, s60, 0x3400000
	v_writelane_b32 v253, s3, 48
	s_addc_u32 s3, s61, 0
	s_add_u32 s4, s62, 0x9e00000
	v_writelane_b32 v253, s3, 49
	s_addc_u32 s5, s63, 0
	v_writelane_b32 v253, s4, 50
	s_nop 1
	v_writelane_b32 v253, s5, 51
	s_add_u32 s4, s60, 0x2000000
	s_addc_u32 s5, s61, 0
	v_writelane_b32 v253, s4, 52
	s_nop 1
	v_writelane_b32 v253, s5, 53
	s_add_u32 s4, s60, 0x2800000
	s_addc_u32 s5, s61, 0
	v_writelane_b32 v253, s4, 54
	s_nop 1
	v_writelane_b32 v253, s5, 55
	s_add_u32 s4, s62, 0x10898000
	s_addc_u32 s5, s63, 0
	v_writelane_b32 v253, s4, 56
	s_nop 1
	v_writelane_b32 v253, s5, 57
	s_add_u32 s4, s62, 0x10318000
	s_addc_u32 s5, s63, 0
	v_writelane_b32 v253, s4, 58
	s_nop 1
	v_writelane_b32 v253, s5, 59
	s_add_u32 s4, s62, 0xfd98000
	s_addc_u32 s5, s63, 0
	v_writelane_b32 v253, s4, 60
	s_nop 1
	v_writelane_b32 v253, s5, 61
	s_add_u32 s4, s62, 0xfb98000
	s_addc_u32 s5, s63, 0
	s_add_u32 s3, s62, 0x80
	v_writelane_b32 v254, s3, 0
	s_addc_u32 s3, s63, 0
	v_writelane_b32 v254, s3, 1
	s_add_u32 s3, s62, 0xf680080
	v_writelane_b32 v254, s3, 2
	s_addc_u32 s3, s63, 0
	v_writelane_b32 v254, s3, 3
	s_add_i32 s3, 0, 0x12ff0
	v_writelane_b32 v253, s4, 62
	v_writelane_b32 v254, s3, 4
	s_add_i32 s3, 0, 0x12ff4
	v_writelane_b32 v253, s5, 63
	v_writelane_b32 v254, s3, 5
	s_add_i32 s4, 0, 0x8200
	v_writelane_b32 v254, s4, 6
	s_add_i32 s4, 0, 0x10500
	v_writelane_b32 v254, s4, 7
	s_add_i32 s4, 0, 0x10700
	v_writelane_b32 v254, s4, 8
	s_add_i32 s4, 0, 0x10600
	v_writelane_b32 v254, s4, 9
	s_add_i32 s4, 0, 0x105fc
	v_writelane_b32 v254, s4, 10
	s_waitcnt lgkmcnt(0)
	v_writelane_b32 v254, s36, 11
	s_movk_i32 s3, 0x6000
	s_add_i32 s84, 0, 0x10400
	v_writelane_b32 v254, s37, 12
	v_writelane_b32 v254, s38, 13
	v_writelane_b32 v254, s39, 14
	v_writelane_b32 v254, s40, 15
	v_writelane_b32 v254, s41, 16
	v_writelane_b32 v254, s42, 17
	v_writelane_b32 v254, s43, 18
	v_writelane_b32 v254, s44, 19
	v_writelane_b32 v254, s45, 20
	v_writelane_b32 v254, s46, 21
	v_writelane_b32 v254, s47, 22
	v_writelane_b32 v254, s48, 23
	v_writelane_b32 v254, s49, 24
	v_writelane_b32 v254, s50, 25
	v_writelane_b32 v254, s51, 26
	s_load_dwordx16 s[36:51], s[0:1], 0x40
	s_waitcnt lgkmcnt(0)
	v_writelane_b32 v254, s36, 27
	s_nop 1
	v_writelane_b32 v254, s37, 28
	v_writelane_b32 v254, s38, 29
	v_writelane_b32 v254, s39, 30
	v_writelane_b32 v254, s40, 31
	v_writelane_b32 v254, s41, 32
	v_writelane_b32 v254, s42, 33
	v_writelane_b32 v254, s43, 34
	v_writelane_b32 v254, s44, 35
	v_writelane_b32 v254, s45, 36
	v_writelane_b32 v254, s46, 37
	v_writelane_b32 v254, s47, 38
	v_writelane_b32 v254, s48, 39
	v_writelane_b32 v254, s49, 40
	v_writelane_b32 v254, s50, 41
	v_writelane_b32 v254, s51, 42
	s_load_dwordx16 s[36:51], s[0:1], 0x80
	s_waitcnt lgkmcnt(0)
	v_writelane_b32 v254, s36, 43
	s_nop 1
	v_writelane_b32 v254, s37, 44
	v_writelane_b32 v254, s38, 45
	v_writelane_b32 v254, s39, 46
	v_writelane_b32 v254, s40, 47
	v_writelane_b32 v254, s41, 48
	v_writelane_b32 v254, s42, 49
	v_writelane_b32 v254, s43, 50
	v_writelane_b32 v254, s44, 51
	v_writelane_b32 v254, s45, 52
	v_writelane_b32 v254, s46, 53
	v_writelane_b32 v254, s47, 54
	v_writelane_b32 v254, s48, 55
	v_writelane_b32 v254, s49, 56
	v_writelane_b32 v254, s50, 57
	v_writelane_b32 v254, s51, 58
	v_writelane_b32 v254, s2, 59
	v_writelane_b32 v254, s6, 60
	s_nop 1
	v_writelane_b32 v254, s7, 61
	s_mov_b32 vcc_lo, 0
	s_nop 0
	v_writelane_b32 v255, vcc_lo, 40
	s_mov_b32 vcc_lo, -1
	s_nop 0
	v_writelane_b32 v255, vcc_lo, 49
	s_branch .LBB0_8

.LBB0_61:
	s_cmp_eq_u32 s17, 1
	s_cbranch_scc0 .Lbar_chk_done
	s_mov_b64 exec, 1
	v_readlane_b32 s4, v252, 4
	v_readlane_b32 s5, v252, 5
	v_mov_b32_e32 v3, 0x3400
	s_nop 3
	global_load_dwordx4 v[4:7], v3, s[4:5] sc1
	global_load_dwordx4 v[8:11], v3, s[4:5] offset:16 sc1
	s_mov_b32 s10, 0
	s_mov_b32 s11, 1
	s_waitcnt vmcnt(0)
	v_readfirstlane_b32 s6, v4
	s_bcnt1_i32_b32 s7, s6
	s_cmp_eq_u32 s7, 1
	s_cselect_b32 s11, s11, 0
	s_or_b32 s10, s10, s6
	v_readfirstlane_b32 s6, v5
	s_bcnt1_i32_b32 s7, s6
	s_cmp_eq_u32 s7, 1
	s_cselect_b32 s11, s11, 0
	s_or_b32 s10, s10, s6
	v_readfirstlane_b32 s6, v6
	s_bcnt1_i32_b32 s7, s6
	s_cmp_eq_u32 s7, 1
	s_cselect_b32 s11, s11, 0
	s_or_b32 s10, s10, s6
	v_readfirstlane_b32 s6, v7
	s_bcnt1_i32_b32 s7, s6
	s_cmp_eq_u32 s7, 1
	s_cselect_b32 s11, s11, 0
	s_or_b32 s10, s10, s6
	v_readfirstlane_b32 s6, v8
	s_bcnt1_i32_b32 s7, s6
	s_cmp_eq_u32 s7, 1
	s_cselect_b32 s11, s11, 0
	s_or_b32 s10, s10, s6
	v_readfirstlane_b32 s6, v9
	s_bcnt1_i32_b32 s7, s6
	s_cmp_eq_u32 s7, 1
	s_cselect_b32 s11, s11, 0
	s_or_b32 s10, s10, s6
	v_readfirstlane_b32 s6, v10
	s_bcnt1_i32_b32 s7, s6
	s_cmp_eq_u32 s7, 1
	s_cselect_b32 s11, s11, 0
	s_or_b32 s10, s10, s6
	v_readfirstlane_b32 s6, v11
	s_bcnt1_i32_b32 s7, s6
	s_cmp_eq_u32 s7, 1
	s_cselect_b32 s11, s11, 0
	s_or_b32 s10, s10, s6
	s_bcnt1_i32_b32 s7, s10
	s_cmp_eq_u32 s7, 8
	s_cselect_b32 s11, s11, 0
	v_readlane_b32 s6, v252, 2
	v_readlane_b32 s7, v252, 3
	s_load_dword s6, s[6:7], 0x0
	s_waitcnt lgkmcnt(0)
	s_and_b32 s6, s6, 63
	s_cmp_eq_u32 s6, 0
	s_cselect_b32 s11, s11, 0
	s_nop 0
	v_writelane_b32 v255, s11, 40
	s_mov_b64 exec, -1
	v_mov_b32_e32 v3, 0x12ff8
	ds_read_b32 v3, v3
	s_getreg_b32 s6, hwreg(HW_REG_XCC_ID, 0, 4)
	s_and_b32 s6, s6, 7
	s_lshl_b32 s6, s6, 8
	s_addk_i32 s6, 0x3500
	v_lshl_add_u32 v4, v198, 2, s6
	global_load_dword v4, v4, s[4:5] sc1
	s_getreg_b32 s7, hwreg(HW_REG_HW_ID, 8, 8)
	s_mov_b32 s100, 0
	s_mov_b32 s101, 0
	s_waitcnt vmcnt(0) lgkmcnt(0)
	v_readfirstlane_b32 s10, v3
	v_and_b32_e32 v5, 0xfdfdfdfd, v4
	v_cmp_ne_u32_e32 vcc, 0, v5
	s_cmp_lg_u64 vcc, 0
	s_cselect_b32 s11, 0, s11
	s_cmp_lt_u32 s10, 2
	s_cselect_b32 s11, s11, 0
	s_lshr_b32 s6, s7, 2
	s_lshl_b64 s[4:5], 1, s6
	s_sub_u32 s4, s4, 1
	s_subb_u32 s5, s5, 0
	v_readlane_b32 s6, v4, s6
	s_and_b32 s7, s7, 3
	s_lshl_b32 s7, s7, 3
	s_bfm_b32 s7, s7, 0
	s_and_b32 s6, s6, s7
	s_bcnt1_i32_b32 s101, s6
	v_bfe_u32 v5, v4, 1, 1
	v_cmp_ne_u32_e32 vcc, 0, v5
	s_bcnt1_i32_b64 s6, vcc
	s_add_u32 s100, s100, s6
	s_and_b64 vcc, vcc, s[4:5]
	s_bcnt1_i32_b64 s6, vcc
	s_add_u32 s101, s101, s6
	v_bfe_u32 v5, v4, 9, 1
	v_cmp_ne_u32_e32 vcc, 0, v5
	s_bcnt1_i32_b64 s6, vcc
	s_add_u32 s100, s100, s6
	s_and_b64 vcc, vcc, s[4:5]
	s_bcnt1_i32_b64 s6, vcc
	s_add_u32 s101, s101, s6
	v_bfe_u32 v5, v4, 17, 1
	v_cmp_ne_u32_e32 vcc, 0, v5
	s_bcnt1_i32_b64 s6, vcc
	s_add_u32 s100, s100, s6
	s_and_b64 vcc, vcc, s[4:5]
	s_bcnt1_i32_b64 s6, vcc
	s_add_u32 s101, s101, s6
	v_bfe_u32 v5, v4, 25, 1
	v_cmp_ne_u32_e32 vcc, 0, v5
	s_bcnt1_i32_b64 s6, vcc
	s_add_u32 s100, s100, s6
	s_and_b64 vcc, vcc, s[4:5]
	s_bcnt1_i32_b64 s6, vcc
	s_add_u32 s101, s101, s6
	s_cmp_eq_u32 s100, 32
	s_cselect_b32 s11, s11, 0
	s_lshl_b32 s10, s10, 8
	s_or_b32 s10, s10, s101
	s_cmp_eq_u32 s11, 1
	s_cselect_b32 s10, s10, -1
	s_nop 0
	v_writelane_b32 v255, s10, 49

.LBB0_86:
	v_mov_b32_e32 v2, v0
	s_mov_b32 s16, s2
	v_readlane_b32 s10, v255, 49
	s_cmp_eq_u32 s10, -1
	s_cbranch_scc1 .Lps_fb
	s_lshr_b32 s11, s10, 8
	s_and_b32 s10, s10, 0xff
	s_and_b32 s16, s2, 7
	s_and_b32 vcc_lo, s10, 7
	s_lshl_b32 vcc_lo, vcc_lo, 3
	s_or_b32 s16, s16, vcc_lo
	s_lshr_b32 s10, s10, 3
	s_lshl_b32 s10, s10, 1
	s_or_b32 s10, s10, s11
	s_lshl_b32 s10, s10, 6
	s_or_b32 s16, s16, s10
.Lps_fb:
	s_cmpk_gt_i32 s16, 0x1ff
	s_cbranch_scc1 .LBB0_91
	v_ashrrev_i32_e32 v3, 6, v2
	v_readlane_b32 s10, v254, 62
	v_readlane_b32 s11, v254, 63
	s_add_u32 s10, s10, s6
	v_lshlrev_b32_e32 v7, 2, v3
	s_addc_u32 s11, s11, s7
	v_and_b32_e32 v7, 4, v7
	v_bfe_u32 v8, v2, 4, 2
	v_and_b32_e32 v9, 7, v2
	s_add_u32 s36, s62, s4
	v_bitop3_b32 v7, v7, v9, v8 bitop3:0x36
	s_addc_u32 s37, s63, s5
	v_lshlrev_b32_e32 v130, 4, v7
	s_lshl_b32 s22, s13, 8
	v_lshl_add_u64 v[68:69], s[10:11], 0, v[130:131]
	s_lshl_b32 s10, s13, 5
	s_lshl_b32 s11, s13, 6
	s_and_b32 s22, s22, 0xfc000
	v_readlane_b32 s25, v254, 0
	v_bfe_u32 v4, v2, 3, 3
	s_add_u32 s4, s25, s4
	v_readlane_b32 s25, v254, 1
	v_lshl_or_b32 v86, v3, 3, v4
	v_lshrrev_b32_e32 v4, 1, v2
	v_bfe_u32 v5, v2, 1, 3
	v_bfe_u32 v6, v2, 5, 1
	v_ashrrev_i32_e32 v8, 7, v2
	v_and_b32_e32 v2, 31, v2
	v_lshlrev_b32_e32 v7, 5, v3
	s_addc_u32 s5, s25, s5
	s_lshl_b32 s25, s13, 1
	v_lshlrev_b32_e32 v90, 7, v2
	v_and_or_b32 v91, v7, 32, v2
	v_bitop3_b32 v2, v6, v5, 2 bitop3:0x36
	s_add_u32 s6, s6, s38
	v_lshlrev_b32_e32 v93, 4, v2
	v_bitop3_b32 v2, v6, v5, 4 bitop3:0x36
	s_addc_u32 s7, s7, s27
	v_readlane_b32 s27, v254, 2
	v_lshl_add_u64 v[66:67], s[36:37], 0, v[130:131]
	v_lshlrev_b32_e32 v9, 2, v6
	v_lshlrev_b32_e32 v87, 10, v3
	s_mul_i32 s36, s13, 0x60
	v_bitop3_b32 v3, v6, v4, 7 bitop3:0x78
	v_lshlrev_b32_e32 v94, 4, v2
	v_bitop3_b32 v2, v6, v5, 6 bitop3:0x36
	s_add_u32 s6, s27, s6
	v_readlane_b32 s27, v254, 3
	v_lshlrev_b32_e32 v88, 4, v3
	v_lshlrev_b32_e32 v89, 13, v8
	v_lshlrev_b32_e32 v92, 7, v91
	v_lshlrev_b32_e32 v95, 4, v2
	v_lshl_or_b32 v96, v8, 6, v9
	s_addc_u32 s7, s27, s7
	v_add_u32_e32 v97, 32, v86
	v_add_u32_e32 v98, 64, v86
	v_add_u32_e32 v99, 0x60, v86
	s_lshl_b32 s92, s10, 1
	s_lshl_b32 s10, s11, 1
	s_lshl_b32 s36, s36, 1
